# P3 early out-proj tiles (critical path of the scan phase): 7 of 10 residual loads prefetched in the tile prologue, counted wait for the rest
# baseline (speedup 1.0000x reference)
.LBB0_642:
	v_bfe_u32 v136, v202, 4, 2
	v_and_b32_e32 v12, 15, v202
	v_lshlrev_b32_e32 v13, 4, v136
	v_lshlrev_b32_e32 v14, 2, v202
	v_lshl_or_b32 v137, s8, 6, v12
	v_lshl_or_b32 v12, v12, 6, v13
	s_lshl_b32 s8, s8, 13
	v_and_b32_e32 v14, 32, v14
	s_and_b32 s26, s9, 3
	v_bitop3_b32 v12, v12, s8, v14 bitop3:0xde
	v_lshlrev_b32_e32 v15, 6, v202
	s_movk_i32 s8, 0x3c0
	v_readlane_b32 s45, v246, 0
	v_and_or_b32 v13, v15, s8, v13
	s_lshl_b32 s8, s26, 12
	s_add_i32 s47, s45, 0x18000
	v_bitop3_b32 v13, s8, v13, v14 bitop3:0xf6
	s_add_i32 s36, s47, s11
	s_mov_b64 s[8:9], 0x80
	v_lshl_add_u64 v[6:7], v[6:7], 0, s[8:9]
	s_mov_b32 m0, s36
	s_add_i32 s37, s36, 0x2000
	s_add_i32 s38, s29, 0x8000
	s_add_i32 s39, s29, 0xa000
	global_load_lds_dwordx4 v[6:7], off
	v_lshl_add_u64 v[4:5], v[4:5], 0, s[8:9]
	s_mov_b32 m0, s37
	s_add_u32 s16, s6, 0x40080
	global_load_lds_dwordx4 v[4:5], off
	v_lshl_add_u64 v[2:3], v[2:3], 0, s[8:9]
	s_mov_b32 m0, s38
	s_addc_u32 s17, s7, 0
	s_add_i32 s48, s45, 0x1c000
	global_load_lds_dwordx4 v[2:3], off
	v_lshl_add_u64 v[0:1], v[0:1], 0, s[8:9]
	s_mov_b32 m0, s39
	s_add_i32 s40, s48, s11
	global_load_lds_dwordx4 v[0:1], off
	v_lshl_add_u64 v[0:1], s[16:17], 0, v[130:131]
	s_mov_b32 m0, s40
	s_add_i32 s41, s40, 0x2000
	global_load_lds_dwordx4 v[0:1], off
	v_lshl_add_u64 v[0:1], s[16:17], 0, v[128:129]
	s_mov_b32 m0, s41
	s_lshl_b32 s10, s10, 19
	global_load_lds_dwordx4 v[0:1], off
	s_waitcnt vmcnt(8)
	s_barrier
	v_lshlrev_b32_e32 v0, 8, v202
	v_and_b32_e32 v0, 0xffff8000, v0
	v_lshlrev_b32_e32 v2, 11, v11
	s_add_u32 s10, s22, s10
	v_or3_b32 v0, v10, v0, v2
	s_addc_u32 s11, s23, 0
	v_add_u32_e32 v0, v0, v9
	v_mov_b32_e32 v1, v131
	v_lshl_add_u64 v[0:1], s[10:11], 0, v[0:1]
	s_mov_b64 s[16:17], 0x159e4080
	v_lshl_add_u64 v[132:133], v[0:1], 0, s[16:17]
	v_lshlrev_b32_e32 v0, 4, v8
	v_and_b32_e32 v0, 0xffff8000, v0
	v_or3_b32 v0, v10, v0, v2
	s_add_u32 s12, s22, s12
	s_waitcnt vmcnt(6)
	v_add_u32_e32 v0, v0, v9
	v_mov_b32_e32 v1, v131
	s_addc_u32 s13, s23, s13
	v_lshl_add_u64 v[0:1], s[10:11], 0, v[0:1]
	s_add_u32 s42, s12, 0x580100
	v_lshl_add_u64 v[134:135], v[0:1], 0, s[16:17]
	s_addc_u32 s43, s13, 0
	s_mov_b32 s44, -2
	s_mov_b64 s[12:13], 0
	v_add_u32_e32 v138, s14, v13
	v_add_u32_e32 v139, s45, v12
	s_add_i32 s45, s29, 0xc000
	s_add_i32 s46, s29, 0xe000
	v_add_u32_e32 v140, s15, v13
	v_add_u32_e32 v141, s47, v13
	v_add_u32_e32 v142, s48, v13
	v_mov_b32_e32 v0, v131
	v_mov_b32_e32 v1, v131
	v_mov_b32_e32 v2, v131
	v_mov_b32_e32 v3, v131
	v_mov_b32_e32 v4, v131
	v_mov_b32_e32 v5, v131
	v_mov_b32_e32 v6, v131
	v_mov_b32_e32 v7, v131
	v_mov_b32_e32 v16, v131
	v_mov_b32_e32 v17, v131
	v_mov_b32_e32 v18, v131
	v_mov_b32_e32 v19, v131
	v_mov_b32_e32 v20, v131
	s_waitcnt lgkmcnt(0)
	v_mov_b32_e32 v21, v131
	v_mov_b32_e32 v22, v131
	v_mov_b32_e32 v23, v131
	v_mov_b32_e32 v32, v131
	v_mov_b32_e32 v33, v131
	v_mov_b32_e32 v34, v131
	v_mov_b32_e32 v35, v131
	v_mov_b32_e32 v36, v131
	v_mov_b32_e32 v37, v131
	v_mov_b32_e32 v38, v131
	v_mov_b32_e32 v39, v131
	v_mov_b32_e32 v48, v131
	v_mov_b32_e32 v49, v131
	v_mov_b32_e32 v50, v131
	v_mov_b32_e32 v51, v131
	v_mov_b32_e32 v52, v131
	v_mov_b32_e32 v53, v131
	v_mov_b32_e32 v54, v131
	v_mov_b32_e32 v55, v131
	v_mov_b32_e32 v8, v131
	v_mov_b32_e32 v9, v131
	v_mov_b32_e32 v10, v131
	v_mov_b32_e32 v11, v131
	v_mov_b32_e32 v12, v131
	v_mov_b32_e32 v13, v131
	v_mov_b32_e32 v14, v131
	v_mov_b32_e32 v15, v131
	v_mov_b32_e32 v24, v131
	v_mov_b32_e32 v25, v131
	v_mov_b32_e32 v26, v131
	v_mov_b32_e32 v27, v131
	v_mov_b32_e32 v28, v131
	v_mov_b32_e32 v29, v131
	v_mov_b32_e32 v30, v131
	v_mov_b32_e32 v31, v131
	v_mov_b32_e32 v40, v131
	v_mov_b32_e32 v41, v131
	v_mov_b32_e32 v42, v131
	v_mov_b32_e32 v43, v131
	v_mov_b32_e32 v44, v131
	v_mov_b32_e32 v45, v131
	v_mov_b32_e32 v46, v131
	v_mov_b32_e32 v47, v131
	v_mov_b32_e32 v56, v131
	v_mov_b32_e32 v57, v131
	v_mov_b32_e32 v58, v131
	v_mov_b32_e32 v59, v131
	v_mov_b32_e32 v60, v131
	v_mov_b32_e32 v61, v131
	v_mov_b32_e32 v62, v131
	v_mov_b32_e32 v63, v131
	v_mov_b32_e32 v64, v131
	v_mov_b32_e32 v65, v131
	v_mov_b32_e32 v66, v131
	v_mov_b32_e32 v67, v131
	v_mov_b32_e32 v68, v131
	v_mov_b32_e32 v69, v131
	v_mov_b32_e32 v70, v131
	v_mov_b32_e32 v71, v131
	v_mov_b32_e32 v80, v131
	v_mov_b32_e32 v81, v131
	v_mov_b32_e32 v82, v131
	v_mov_b32_e32 v83, v131
	v_mov_b32_e32 v84, v131
	v_mov_b32_e32 v85, v131
	v_mov_b32_e32 v86, v131
	v_mov_b32_e32 v87, v131
	v_mov_b32_e32 v96, v131
	v_mov_b32_e32 v97, v131
	v_mov_b32_e32 v98, v131
	v_mov_b32_e32 v99, v131
	v_mov_b32_e32 v100, v131
	v_mov_b32_e32 v101, v131
	v_mov_b32_e32 v102, v131
	v_mov_b32_e32 v103, v131
	v_mov_b32_e32 v112, v131
	v_mov_b32_e32 v113, v131
	v_mov_b32_e32 v114, v131
	v_mov_b32_e32 v115, v131
	v_mov_b32_e32 v116, v131
	v_mov_b32_e32 v117, v131
	v_mov_b32_e32 v118, v131
	v_mov_b32_e32 v119, v131
	v_mov_b32_e32 v72, v131
	v_mov_b32_e32 v73, v131
	v_mov_b32_e32 v74, v131
	v_mov_b32_e32 v75, v131
	v_mov_b32_e32 v76, v131
	v_mov_b32_e32 v77, v131
	v_mov_b32_e32 v78, v131
	v_mov_b32_e32 v79, v131
	v_mov_b32_e32 v88, v131
	v_mov_b32_e32 v89, v131
	v_mov_b32_e32 v90, v131
	v_mov_b32_e32 v91, v131
	v_mov_b32_e32 v92, v131
	v_mov_b32_e32 v93, v131
	v_mov_b32_e32 v94, v131
	v_mov_b32_e32 v95, v131
	v_mov_b32_e32 v104, v131
	v_mov_b32_e32 v105, v131
	v_mov_b32_e32 v106, v131
	v_mov_b32_e32 v107, v131
	v_mov_b32_e32 v108, v131
	v_mov_b32_e32 v109, v131
	v_mov_b32_e32 v110, v131
	v_mov_b32_e32 v111, v131
	v_mov_b32_e32 v120, v131
	v_mov_b32_e32 v121, v131
	v_mov_b32_e32 v122, v131
	v_mov_b32_e32 v123, v131
	v_mov_b32_e32 v124, v131
	v_mov_b32_e32 v125, v131
	v_mov_b32_e32 v126, v131
	v_mov_b32_e32 v127, v131
	v_lshlrev_b32_e32 v203, 3, v136
	v_lshl_or_b32 v203, s26, 6, v203
	v_lshl_or_b32 v203, s0, 8, v203
	v_lshlrev_b32_e32 v203, 1, v203
	v_lshl_add_u32 v247, s27, 8, v137
	v_lshl_add_u32 v203, v247, 11, v203
	s_add_u32 s72, s22, 0x1c00000
	s_addc_u32 s73, s23, 0
	s_add_u32 s74, s72, 0x8000
	s_addc_u32 s75, s73, 0
	s_add_u32 s76, s72, 0x10000
	s_addc_u32 s77, s73, 0
	s_add_u32 s78, s72, 0x18000
	s_addc_u32 s79, s73, 0
	global_load_dwordx4 v[220:223], v203, s[72:73]
	global_load_dwordx4 v[224:227], v203, s[72:73] offset:64
	global_load_dwordx4 v[228:231], v203, s[74:75]
	global_load_dwordx4 v[232:235], v203, s[74:75] offset:64
	global_load_dwordx4 v[236:239], v203, s[76:77]
	global_load_dwordx4 v[240:243], v203, s[76:77] offset:64
	global_load_dwordx4 v[252:255], v203, s[78:79]
	s_barrier
	s_waitcnt vmcnt(0)
.LBB0_643:
	s_add_u32 s14, s10, s12
	ds_read_b128 v[144:147], v138
	ds_read_b128 v[148:151], v138 offset:1024
	ds_read_b128 v[152:155], v138 offset:2048
	ds_read_b128 v[156:159], v138 offset:3072
	s_addc_u32 s15, s11, s13
	s_add_u32 s14, s14, 0x159a4100
	s_addc_u32 s15, s15, 0
	s_add_u32 s47, s42, s12
	s_addc_u32 s48, s43, s13
	s_cmpk_eq_i32 s12, 0x700
	s_cselect_b32 s17, s5, s15
	s_cselect_b32 s16, s4, s14
	s_cselect_b32 s15, s7, s48
	s_cselect_b32 s14, s6, s47
	s_mov_b32 m0, s45
	v_lshl_add_u64 v[192:193], v[132:133], 0, s[12:13]
	ds_read_b128 v[160:163], v139
	ds_read_b128 v[164:167], v139 offset:1024
	ds_read_b128 v[168:171], v139 offset:2048
	ds_read_b128 v[172:175], v139 offset:3072
	ds_read_b128 v[176:179], v139 offset:4096
	ds_read_b128 v[180:183], v139 offset:5120
	ds_read_b128 v[184:187], v139 offset:6144
	ds_read_b128 v[188:191], v139 offset:7168
	global_load_lds_dwordx4 v[192:193], off
	v_lshl_add_u64 v[192:193], v[134:135], 0, s[12:13]
	s_mov_b32 m0, s46
	s_nop 0
	global_load_lds_dwordx4 v[192:193], off
	ds_read_b128 v[192:195], v140
	ds_read_b128 v[196:199], v140 offset:1024
	ds_read_b128 v[204:207], v140 offset:2048
	ds_read_b128 v[208:211], v140 offset:3072
	s_waitcnt lgkmcnt(0)
	s_waitcnt vmcnt(8)
	s_barrier
	s_setprio 1
	v_mfma_f32_16x16x32_bf16 v[124:127], v[144:147], v[160:163], v[124:127]
	v_mfma_f32_16x16x32_bf16 v[120:123], v[152:155], v[160:163], v[120:123]
	v_mfma_f32_16x16x32_bf16 v[108:111], v[144:147], v[168:171], v[108:111]
	v_mfma_f32_16x16x32_bf16 v[104:107], v[152:155], v[168:171], v[104:107]
	v_mfma_f32_16x16x32_bf16 v[92:95], v[144:147], v[176:179], v[92:95]
	v_mfma_f32_16x16x32_bf16 v[88:91], v[152:155], v[176:179], v[88:91]
	v_mfma_f32_16x16x32_bf16 v[76:79], v[144:147], v[184:187], v[76:79]
	v_mfma_f32_16x16x32_bf16 v[72:75], v[152:155], v[184:187], v[72:75]
	v_mfma_f32_16x16x32_bf16 v[124:127], v[148:151], v[164:167], v[124:127]
	v_mfma_f32_16x16x32_bf16 v[120:123], v[156:159], v[164:167], v[120:123]
	v_mfma_f32_16x16x32_bf16 v[108:111], v[148:151], v[172:175], v[108:111]
	v_mfma_f32_16x16x32_bf16 v[104:107], v[156:159], v[172:175], v[104:107]
	v_mfma_f32_16x16x32_bf16 v[92:95], v[148:151], v[180:183], v[92:95]
	v_mfma_f32_16x16x32_bf16 v[88:91], v[156:159], v[180:183], v[88:91]
	v_mfma_f32_16x16x32_bf16 v[76:79], v[148:151], v[188:191], v[76:79]
	v_mfma_f32_16x16x32_bf16 v[72:75], v[156:159], v[188:191], v[72:75]
	v_mfma_f32_16x16x32_bf16 v[116:119], v[192:195], v[160:163], v[116:119]
	v_mfma_f32_16x16x32_bf16 v[112:115], v[204:207], v[160:163], v[112:115]
	v_mfma_f32_16x16x32_bf16 v[100:103], v[192:195], v[168:171], v[100:103]
	v_mfma_f32_16x16x32_bf16 v[96:99], v[204:207], v[168:171], v[96:99]
	v_mfma_f32_16x16x32_bf16 v[84:87], v[192:195], v[176:179], v[84:87]
	v_mfma_f32_16x16x32_bf16 v[80:83], v[204:207], v[176:179], v[80:83]
	v_mfma_f32_16x16x32_bf16 v[68:71], v[192:195], v[184:187], v[68:71]
	v_mfma_f32_16x16x32_bf16 v[64:67], v[204:207], v[184:187], v[64:67]
	v_mfma_f32_16x16x32_bf16 v[116:119], v[196:199], v[164:167], v[116:119]
	v_mfma_f32_16x16x32_bf16 v[112:115], v[208:211], v[164:167], v[112:115]
	v_mfma_f32_16x16x32_bf16 v[100:103], v[196:199], v[172:175], v[100:103]
	v_mfma_f32_16x16x32_bf16 v[96:99], v[208:211], v[172:175], v[96:99]
	v_mfma_f32_16x16x32_bf16 v[84:87], v[196:199], v[180:183], v[84:87]
	v_mfma_f32_16x16x32_bf16 v[80:83], v[208:211], v[180:183], v[80:83]
	v_mfma_f32_16x16x32_bf16 v[68:71], v[196:199], v[188:191], v[68:71]
	v_mfma_f32_16x16x32_bf16 v[64:67], v[208:211], v[188:191], v[64:67]
	s_setprio 0
	s_barrier
	ds_read_b128 v[160:163], v139 offset:16384
	ds_read_b128 v[164:167], v139 offset:17408
	ds_read_b128 v[168:171], v139 offset:18432
	ds_read_b128 v[172:175], v139 offset:19456
	ds_read_b128 v[176:179], v139 offset:20480
	ds_read_b128 v[180:183], v139 offset:21504
	ds_read_b128 v[184:187], v139 offset:22528
	ds_read_b128 v[188:191], v139 offset:23552
	s_mov_b32 m0, s1
	v_lshl_add_u64 v[200:201], s[14:15], 0, v[130:131]
	global_load_lds_dwordx4 v[200:201], off
	v_lshl_add_u64 v[212:213], s[14:15], 0, v[128:129]
	s_mov_b32 m0, s28
	s_nop 0
	global_load_lds_dwordx4 v[212:213], off
	s_mov_b32 m0, s29
	v_lshl_add_u64 v[214:215], s[16:17], 0, v[130:131]
	global_load_lds_dwordx4 v[214:215], off
	v_lshl_add_u64 v[216:217], s[16:17], 0, v[128:129]
	s_mov_b32 m0, s30
	s_nop 0
	global_load_lds_dwordx4 v[216:217], off
	s_add_u32 s48, s14, 0x40000
	s_addc_u32 s49, s15, 0
	s_mov_b32 m0, s31
	v_lshl_add_u64 v[248:249], s[48:49], 0, v[130:131]
	global_load_lds_dwordx4 v[248:249], off
	v_lshl_add_u64 v[248:249], s[48:49], 0, v[128:129]
	s_mov_b32 m0, s33
	s_nop 0
	global_load_lds_dwordx4 v[248:249], off
	s_waitcnt lgkmcnt(0)
	s_waitcnt vmcnt(8)
	s_barrier
	s_setprio 1
	v_mfma_f32_16x16x32_bf16 v[60:63], v[144:147], v[160:163], v[60:63]
	v_mfma_f32_16x16x32_bf16 v[56:59], v[152:155], v[160:163], v[56:59]
	v_mfma_f32_16x16x32_bf16 v[44:47], v[144:147], v[168:171], v[44:47]
	v_mfma_f32_16x16x32_bf16 v[40:43], v[152:155], v[168:171], v[40:43]
	v_mfma_f32_16x16x32_bf16 v[28:31], v[144:147], v[176:179], v[28:31]
	v_mfma_f32_16x16x32_bf16 v[24:27], v[152:155], v[176:179], v[24:27]
	v_mfma_f32_16x16x32_bf16 v[12:15], v[144:147], v[184:187], v[12:15]
	v_mfma_f32_16x16x32_bf16 v[8:11], v[152:155], v[184:187], v[8:11]
	v_mfma_f32_16x16x32_bf16 v[60:63], v[148:151], v[164:167], v[60:63]
	v_mfma_f32_16x16x32_bf16 v[56:59], v[156:159], v[164:167], v[56:59]
	v_mfma_f32_16x16x32_bf16 v[44:47], v[148:151], v[172:175], v[44:47]
	v_mfma_f32_16x16x32_bf16 v[40:43], v[156:159], v[172:175], v[40:43]
	v_mfma_f32_16x16x32_bf16 v[28:31], v[148:151], v[180:183], v[28:31]
	v_mfma_f32_16x16x32_bf16 v[24:27], v[156:159], v[180:183], v[24:27]
	v_mfma_f32_16x16x32_bf16 v[12:15], v[148:151], v[188:191], v[12:15]
	v_mfma_f32_16x16x32_bf16 v[8:11], v[156:159], v[188:191], v[8:11]
	v_mfma_f32_16x16x32_bf16 v[52:55], v[192:195], v[160:163], v[52:55]
	v_mfma_f32_16x16x32_bf16 v[48:51], v[204:207], v[160:163], v[48:51]
	v_mfma_f32_16x16x32_bf16 v[36:39], v[192:195], v[168:171], v[36:39]
	v_mfma_f32_16x16x32_bf16 v[32:35], v[204:207], v[168:171], v[32:35]
	v_mfma_f32_16x16x32_bf16 v[20:23], v[192:195], v[176:179], v[20:23]
	v_mfma_f32_16x16x32_bf16 v[16:19], v[204:207], v[176:179], v[16:19]
	v_mfma_f32_16x16x32_bf16 v[4:7], v[192:195], v[184:187], v[4:7]
	v_mfma_f32_16x16x32_bf16 v[0:3], v[204:207], v[184:187], v[0:3]
	v_mfma_f32_16x16x32_bf16 v[52:55], v[196:199], v[164:167], v[52:55]
	v_mfma_f32_16x16x32_bf16 v[48:51], v[208:211], v[164:167], v[48:51]
	v_mfma_f32_16x16x32_bf16 v[36:39], v[196:199], v[172:175], v[36:39]
	v_mfma_f32_16x16x32_bf16 v[32:35], v[208:211], v[172:175], v[32:35]
	v_mfma_f32_16x16x32_bf16 v[20:23], v[196:199], v[180:183], v[20:23]
	v_mfma_f32_16x16x32_bf16 v[16:19], v[208:211], v[180:183], v[16:19]
	v_mfma_f32_16x16x32_bf16 v[4:7], v[196:199], v[188:191], v[4:7]
	v_mfma_f32_16x16x32_bf16 v[0:3], v[208:211], v[188:191], v[0:3]
	s_setprio 0
	s_barrier
	ds_read_b128 v[144:147], v141
	ds_read_b128 v[148:151], v141 offset:1024
	ds_read_b128 v[152:155], v141 offset:2048
	ds_read_b128 v[156:159], v141 offset:3072
	s_add_u32 s16, s16, 0x40000
	s_addc_u32 s17, s17, 0
	s_mov_b32 m0, s34
	v_lshl_add_u64 v[192:193], s[16:17], 0, v[130:131]
	ds_read_b128 v[160:163], v139 offset:32768
	ds_read_b128 v[164:167], v139 offset:33792
	ds_read_b128 v[168:171], v139 offset:34816
	ds_read_b128 v[172:175], v139 offset:35840
	ds_read_b128 v[176:179], v139 offset:36864
	ds_read_b128 v[180:183], v139 offset:37888
	ds_read_b128 v[184:187], v139 offset:38912
	ds_read_b128 v[188:191], v139 offset:39936
	global_load_lds_dwordx4 v[192:193], off
	v_lshl_add_u64 v[192:193], s[16:17], 0, v[128:129]
	s_mov_b32 m0, s35
	s_nop 0
	global_load_lds_dwordx4 v[192:193], off
	ds_read_b128 v[192:195], v142
	ds_read_b128 v[196:199], v142 offset:1024
	ds_read_b128 v[204:207], v142 offset:2048
	ds_read_b128 v[208:211], v142 offset:3072
	s_waitcnt lgkmcnt(0)
	s_waitcnt vmcnt(8)
	s_barrier
	s_setprio 1
	v_mfma_f32_16x16x32_bf16 v[124:127], v[144:147], v[160:163], v[124:127]
	v_mfma_f32_16x16x32_bf16 v[120:123], v[152:155], v[160:163], v[120:123]
	v_mfma_f32_16x16x32_bf16 v[108:111], v[144:147], v[168:171], v[108:111]
	v_mfma_f32_16x16x32_bf16 v[104:107], v[152:155], v[168:171], v[104:107]
	v_mfma_f32_16x16x32_bf16 v[92:95], v[144:147], v[176:179], v[92:95]
	v_mfma_f32_16x16x32_bf16 v[88:91], v[152:155], v[176:179], v[88:91]
	v_mfma_f32_16x16x32_bf16 v[76:79], v[144:147], v[184:187], v[76:79]
	v_mfma_f32_16x16x32_bf16 v[72:75], v[152:155], v[184:187], v[72:75]
	v_mfma_f32_16x16x32_bf16 v[124:127], v[148:151], v[164:167], v[124:127]
	v_mfma_f32_16x16x32_bf16 v[120:123], v[156:159], v[164:167], v[120:123]
	v_mfma_f32_16x16x32_bf16 v[108:111], v[148:151], v[172:175], v[108:111]
	v_mfma_f32_16x16x32_bf16 v[104:107], v[156:159], v[172:175], v[104:107]
	v_mfma_f32_16x16x32_bf16 v[92:95], v[148:151], v[180:183], v[92:95]
	v_mfma_f32_16x16x32_bf16 v[88:91], v[156:159], v[180:183], v[88:91]
	v_mfma_f32_16x16x32_bf16 v[76:79], v[148:151], v[188:191], v[76:79]
	v_mfma_f32_16x16x32_bf16 v[72:75], v[156:159], v[188:191], v[72:75]
	v_mfma_f32_16x16x32_bf16 v[116:119], v[192:195], v[160:163], v[116:119]
	v_mfma_f32_16x16x32_bf16 v[112:115], v[204:207], v[160:163], v[112:115]
	v_mfma_f32_16x16x32_bf16 v[100:103], v[192:195], v[168:171], v[100:103]
	v_mfma_f32_16x16x32_bf16 v[96:99], v[204:207], v[168:171], v[96:99]
	v_mfma_f32_16x16x32_bf16 v[84:87], v[192:195], v[176:179], v[84:87]
	v_mfma_f32_16x16x32_bf16 v[80:83], v[204:207], v[176:179], v[80:83]
	v_mfma_f32_16x16x32_bf16 v[68:71], v[192:195], v[184:187], v[68:71]
	v_mfma_f32_16x16x32_bf16 v[64:67], v[204:207], v[184:187], v[64:67]
	v_mfma_f32_16x16x32_bf16 v[116:119], v[196:199], v[164:167], v[116:119]
	v_mfma_f32_16x16x32_bf16 v[112:115], v[208:211], v[164:167], v[112:115]
	v_mfma_f32_16x16x32_bf16 v[100:103], v[196:199], v[172:175], v[100:103]
	v_mfma_f32_16x16x32_bf16 v[96:99], v[208:211], v[172:175], v[96:99]
	v_mfma_f32_16x16x32_bf16 v[84:87], v[196:199], v[180:183], v[84:87]
	v_mfma_f32_16x16x32_bf16 v[80:83], v[208:211], v[180:183], v[80:83]
	v_mfma_f32_16x16x32_bf16 v[68:71], v[196:199], v[188:191], v[68:71]
	v_mfma_f32_16x16x32_bf16 v[64:67], v[208:211], v[188:191], v[64:67]
	s_setprio 0
	s_barrier
	ds_read_b128 v[160:163], v139 offset:49152
	ds_read_b128 v[164:167], v139 offset:50176
	ds_read_b128 v[168:171], v139 offset:51200
	ds_read_b128 v[172:175], v139 offset:52224
	ds_read_b128 v[176:179], v139 offset:53248
	ds_read_b128 v[180:183], v139 offset:54272
	ds_read_b128 v[184:187], v139 offset:55296
	ds_read_b128 v[188:191], v139 offset:56320
	s_mov_b32 m0, s36
	v_lshl_add_u64 v[200:201], v[200:201], 0, s[8:9]
	global_load_lds_dwordx4 v[200:201], off
	v_lshl_add_u64 v[200:201], v[212:213], 0, s[8:9]
	s_mov_b32 m0, s37
	s_nop 0
	global_load_lds_dwordx4 v[200:201], off
	s_mov_b32 m0, s38
	v_lshl_add_u64 v[200:201], v[214:215], 0, s[8:9]
	global_load_lds_dwordx4 v[200:201], off
	v_lshl_add_u64 v[200:201], v[216:217], 0, s[8:9]
	s_mov_b32 m0, s39
	s_nop 0
	global_load_lds_dwordx4 v[200:201], off
	s_add_u32 s14, s14, 0x40080
	s_addc_u32 s15, s15, 0
	s_mov_b32 m0, s40
	v_lshl_add_u64 v[248:249], s[14:15], 0, v[130:131]
	global_load_lds_dwordx4 v[248:249], off
	v_lshl_add_u64 v[248:249], s[14:15], 0, v[128:129]
	s_mov_b32 m0, s41
	s_nop 0
	global_load_lds_dwordx4 v[248:249], off
	s_waitcnt lgkmcnt(0)
	s_waitcnt vmcnt(8)
	s_barrier
	s_setprio 1
	v_mfma_f32_16x16x32_bf16 v[60:63], v[144:147], v[160:163], v[60:63]
	v_mfma_f32_16x16x32_bf16 v[56:59], v[152:155], v[160:163], v[56:59]
	v_mfma_f32_16x16x32_bf16 v[44:47], v[144:147], v[168:171], v[44:47]
	v_mfma_f32_16x16x32_bf16 v[40:43], v[152:155], v[168:171], v[40:43]
	v_mfma_f32_16x16x32_bf16 v[28:31], v[144:147], v[176:179], v[28:31]
	v_mfma_f32_16x16x32_bf16 v[24:27], v[152:155], v[176:179], v[24:27]
	v_mfma_f32_16x16x32_bf16 v[12:15], v[144:147], v[184:187], v[12:15]
	v_mfma_f32_16x16x32_bf16 v[8:11], v[152:155], v[184:187], v[8:11]
	v_mfma_f32_16x16x32_bf16 v[60:63], v[148:151], v[164:167], v[60:63]
	v_mfma_f32_16x16x32_bf16 v[56:59], v[156:159], v[164:167], v[56:59]
	v_mfma_f32_16x16x32_bf16 v[44:47], v[148:151], v[172:175], v[44:47]
	v_mfma_f32_16x16x32_bf16 v[40:43], v[156:159], v[172:175], v[40:43]
	v_mfma_f32_16x16x32_bf16 v[28:31], v[148:151], v[180:183], v[28:31]
	v_mfma_f32_16x16x32_bf16 v[24:27], v[156:159], v[180:183], v[24:27]
	v_mfma_f32_16x16x32_bf16 v[12:15], v[148:151], v[188:191], v[12:15]
	v_mfma_f32_16x16x32_bf16 v[8:11], v[156:159], v[188:191], v[8:11]
	v_mfma_f32_16x16x32_bf16 v[52:55], v[192:195], v[160:163], v[52:55]
	v_mfma_f32_16x16x32_bf16 v[48:51], v[204:207], v[160:163], v[48:51]
	v_mfma_f32_16x16x32_bf16 v[36:39], v[192:195], v[168:171], v[36:39]
	v_mfma_f32_16x16x32_bf16 v[32:35], v[204:207], v[168:171], v[32:35]
	v_mfma_f32_16x16x32_bf16 v[20:23], v[192:195], v[176:179], v[20:23]
	v_mfma_f32_16x16x32_bf16 v[16:19], v[204:207], v[176:179], v[16:19]
	v_mfma_f32_16x16x32_bf16 v[4:7], v[192:195], v[184:187], v[4:7]
	v_mfma_f32_16x16x32_bf16 v[0:3], v[204:207], v[184:187], v[0:3]
	v_mfma_f32_16x16x32_bf16 v[52:55], v[196:199], v[164:167], v[52:55]
	v_mfma_f32_16x16x32_bf16 v[48:51], v[208:211], v[164:167], v[48:51]
	v_mfma_f32_16x16x32_bf16 v[36:39], v[196:199], v[172:175], v[36:39]
	v_mfma_f32_16x16x32_bf16 v[32:35], v[208:211], v[172:175], v[32:35]
	v_mfma_f32_16x16x32_bf16 v[20:23], v[196:199], v[180:183], v[20:23]
	v_mfma_f32_16x16x32_bf16 v[16:19], v[208:211], v[180:183], v[16:19]
	v_mfma_f32_16x16x32_bf16 v[4:7], v[196:199], v[188:191], v[4:7]
	v_mfma_f32_16x16x32_bf16 v[0:3], v[208:211], v[188:191], v[0:3]
	s_setprio 0
	s_add_i32 s44, s44, 2
	s_add_u32 s12, s12, 0x100
	s_addc_u32 s13, s13, 0
	s_cmp_gt_u32 s44, 13
	s_barrier
	s_cbranch_scc0 .LBB0_643
	v_lshlrev_b32_e32 v128, 3, v136
	v_lshl_or_b32 v128, s26, 6, v128
	s_add_u32 s4, s22, 0x1c00000
	v_lshl_or_b32 v128, s0, 8, v128
	v_mov_b32_e32 v165, 0
	s_addc_u32 s5, s23, 0
	v_lshl_add_u32 v160, s27, 8, v137
	v_lshlrev_b32_e32 v164, 1, v128
	v_mov_b32_e32 v161, v165
	v_lshl_add_u64 v[128:129], s[4:5], 0, v[164:165]
	v_lshlrev_b64 v[174:175], 11, v[160:161]
	v_lshl_add_u64 v[130:131], v[128:129], 0, v[174:175]
	v_mov_b32_e32 v176, v220
	v_mov_b32_e32 v177, v221
	v_mov_b32_e32 v178, v222
	v_mov_b32_e32 v179, v223
	v_mov_b32_e32 v180, v224
	v_mov_b32_e32 v181, v225
	v_mov_b32_e32 v182, v226
	v_mov_b32_e32 v183, v227
	v_or_b32_e32 v130, 16, v160
	v_mov_b32_e32 v131, v165
	v_add_u32_e32 v168, 0x80, v160
	v_mov_b32_e32 v169, v165
	v_or_b32_e32 v132, 32, v160
	v_mov_b32_e32 v133, v165
	v_lshlrev_b64 v[172:173], 11, v[130:131]
	v_lshlrev_b64 v[130:131], 11, v[168:169]
	v_or_b32_e32 v134, 48, v160
	v_mov_b32_e32 v135, v165
	v_lshlrev_b64 v[170:171], 11, v[132:133]
	v_lshl_add_u64 v[130:131], s[4:5], 0, v[130:131]
	v_cmp_eq_u32_e32 vcc, 0, v136
	v_lshlrev_b64 v[166:167], 11, v[134:135]
	v_lshl_add_u64 v[162:163], v[130:131], 0, v[164:165]
	v_lshl_add_u64 v[136:137], v[128:129], 0, v[172:173]
	v_lshl_add_u64 v[138:139], v[128:129], 0, v[170:171]
	v_lshl_add_u64 v[184:185], v[128:129], 0, v[166:167]
	global_load_dwordx4 v[132:135], v[162:163], off
	global_load_dwordx4 v[128:131], v[162:163], off offset:64
	v_mov_b32_e32 v156, v228
	v_mov_b32_e32 v157, v229
	v_mov_b32_e32 v158, v230
	v_mov_b32_e32 v159, v231
	v_mov_b32_e32 v152, v232
	v_mov_b32_e32 v153, v233
	v_mov_b32_e32 v154, v234
	v_mov_b32_e32 v155, v235
	v_mov_b32_e32 v148, v236
	v_mov_b32_e32 v149, v237
	v_mov_b32_e32 v150, v238
	v_mov_b32_e32 v151, v239
	v_mov_b32_e32 v144, v240
	v_mov_b32_e32 v145, v241
	v_mov_b32_e32 v146, v242
	v_mov_b32_e32 v147, v243
	v_mov_b32_e32 v140, v252
	v_mov_b32_e32 v141, v253
	v_mov_b32_e32 v142, v254
	v_mov_b32_e32 v143, v255
	s_nop 0
	global_load_dwordx4 v[136:139], v[184:185], off offset:64
	v_mbcnt_lo_u32_b32 v186, -1, 0
	v_mbcnt_hi_u32_b32 v169, -1, v186
	v_and_b32_e32 v185, 64, v169
	v_xor_b32_e32 v184, 16, v169
	v_add_u32_e32 v185, 64, v185
	v_xor_b32_e32 v186, 32, v169
	v_cmp_lt_i32_e64 s[0:1], v184, v185
	v_lshl_add_u64 v[174:175], s[4:5], 0, v[174:175]
	s_add_u32 s6, s22, 0x18ba4000
	v_cndmask_b32_e64 v187, v169, v184, s[0:1]
	v_cmp_lt_i32_e64 s[0:1], v186, v185
	v_lshl_add_u64 v[184:185], v[174:175], 0, v[164:165]
	v_lshlrev_b32_e32 v174, 2, v187
	v_cndmask_b32_e64 v169, v169, v186, s[0:1]
	v_lshlrev_b32_e32 v169, 2, v169
	s_addc_u32 s7, s23, 0
	s_and_b32 s8, s25, -4
	s_or_b32 s9, s26, s8
	s_mul_hi_u32 s8, s9, 0x21000
	s_mul_i32 s9, s9, 0x21000
	v_lshlrev_b32_e32 v186, 16, v176
	v_and_b32_e32 v187, 0xffff0000, v176
	v_lshlrev_b32_e32 v176, 16, v177
	v_and_b32_e32 v177, 0xffff0000, v177
	v_lshlrev_b32_e32 v192, 16, v182
	v_and_b32_e32 v193, 0xffff0000, v182
	v_lshlrev_b32_e32 v182, 16, v183
	v_and_b32_e32 v183, 0xffff0000, v183
	v_pk_add_f32 v[126:127], v[126:127], v[176:177]
	v_pk_add_f32 v[124:125], v[124:125], v[186:187]
	v_lshlrev_b32_e32 v188, 16, v178
	v_and_b32_e32 v189, 0xffff0000, v178
	v_lshlrev_b32_e32 v178, 16, v179
	v_and_b32_e32 v179, 0xffff0000, v179
	v_pk_add_f32 v[176:177], v[114:115], v[182:183]
	v_mul_f32_e32 v114, v125, v125
	v_mul_f32_e32 v115, v127, v127
	v_pk_add_f32 v[122:123], v[122:123], v[178:179]
	v_pk_add_f32 v[120:121], v[120:121], v[188:189]
	v_fmac_f32_e32 v114, v124, v124
	v_fmac_f32_e32 v115, v126, v126
	v_pk_add_f32 v[178:179], v[112:113], v[192:193]
	v_cvt_pk_bf16_f32 v112, v124, v125
	v_add_f32_e32 v114, v114, v115
	v_mul_f32_e32 v115, v121, v121
	v_mul_f32_e32 v124, v123, v123
	v_lshlrev_b32_e32 v190, 16, v180
	v_and_b32_e32 v191, 0xffff0000, v180
	v_lshlrev_b32_e32 v180, 16, v181
	v_and_b32_e32 v181, 0xffff0000, v181
	v_fmac_f32_e32 v115, v120, v120
	v_fmac_f32_e32 v124, v122, v122
	v_pk_add_f32 v[118:119], v[118:119], v[180:181]
	v_pk_add_f32 v[116:117], v[116:117], v[190:191]
	v_add_f32_e32 v115, v115, v124
	v_add_f32_e32 v114, v114, v115
	v_mul_f32_e32 v115, v117, v117
	v_mul_f32_e32 v124, v119, v119
	v_fmac_f32_e32 v115, v116, v116
	v_fmac_f32_e32 v124, v118, v118
	v_add_f32_e32 v115, v115, v124
	v_mul_f32_e32 v124, v179, v179
	v_mul_f32_e32 v125, v177, v177
	v_fmac_f32_e32 v124, v178, v178
	v_fmac_f32_e32 v125, v176, v176
	v_add_f32_e32 v124, v124, v125
	v_add_f32_e32 v115, v115, v124
	v_add_f32_e32 v124, v114, v115
	ds_bpermute_b32 v125, v174, v124
	v_cvt_pk_bf16_f32 v113, v126, v127
	v_cvt_pk_bf16_f32 v114, v120, v121
	v_cvt_pk_bf16_f32 v115, v122, v123
	global_store_dwordx4 v[184:185], v[112:115], off
	s_waitcnt lgkmcnt(0)
	s_nop 0
	v_add_f32_e32 v112, v124, v125
	ds_bpermute_b32 v113, v169, v112
	v_cvt_pk_bf16_f32 v114, v116, v117
	v_cvt_pk_bf16_f32 v115, v118, v119
	v_cvt_pk_bf16_f32 v116, v178, v179
	v_cvt_pk_bf16_f32 v117, v176, v177
	global_store_dwordx4 v[184:185], v[114:117], off offset:64
	s_and_saveexec_b64 s[0:1], vcc
	s_cbranch_execz .LBB0_646
	s_add_u32 s10, s6, s9
	s_addc_u32 s11, s7, s8
	s_waitcnt lgkmcnt(0)
	v_add_f32_e32 v114, v112, v113
	v_lshl_add_u64 v[112:113], v[160:161], 2, s[10:11]
	global_store_dword v[112:113], v114, off

.LBB0_650:
	s_or_b64 exec, exec, s[0:1]
	v_or_b32_e32 v80, 48, v168
	s_waitcnt lgkmcnt(0)
	v_mov_b32_e32 v81, v165
	v_lshlrev_b64 v[80:81], 11, v[80:81]
	v_lshl_add_u64 v[80:81], s[4:5], 0, v[80:81]
	v_lshl_add_u64 v[88:89], v[80:81], 0, v[164:165]
	global_load_dwordx4 v[84:87], v[88:89], off
	global_load_dwordx4 v[80:83], v[88:89], off offset:64
	v_lshlrev_b32_e32 v92, 16, v141
	v_and_b32_e32 v93, 0xffff0000, v141
	v_lshlrev_b32_e32 v90, 16, v140
	v_and_b32_e32 v91, 0xffff0000, v140
	v_pk_add_f32 v[78:79], v[78:79], v[92:93]
	v_lshlrev_b32_e32 v92, 16, v143
	v_and_b32_e32 v93, 0xffff0000, v143
	v_pk_add_f32 v[76:77], v[76:77], v[90:91]
	v_lshlrev_b32_e32 v90, 16, v142
	v_and_b32_e32 v91, 0xffff0000, v142
	v_pk_add_f32 v[74:75], v[74:75], v[92:93]
	s_waitcnt vmcnt(14)
	v_lshlrev_b32_e32 v92, 16, v137
	v_and_b32_e32 v93, 0xffff0000, v137
	v_pk_add_f32 v[72:73], v[72:73], v[90:91]
	v_lshlrev_b32_e32 v90, 16, v136
	v_and_b32_e32 v91, 0xffff0000, v136
	v_pk_add_f32 v[70:71], v[70:71], v[92:93]
	v_lshlrev_b32_e32 v92, 16, v139
	v_and_b32_e32 v93, 0xffff0000, v139
	v_pk_add_f32 v[68:69], v[68:69], v[90:91]
	v_lshlrev_b32_e32 v90, 16, v138
	v_and_b32_e32 v91, 0xffff0000, v138
	v_pk_add_f32 v[92:93], v[66:67], v[92:93]
	v_mul_f32_e32 v66, v77, v77
	v_mul_f32_e32 v67, v79, v79
	v_pk_add_f32 v[90:91], v[64:65], v[90:91]
	v_lshl_add_u64 v[64:65], s[4:5], 0, v[166:167]
	v_fmac_f32_e32 v66, v76, v76
	v_fmac_f32_e32 v67, v78, v78
	v_lshl_add_u64 v[94:95], v[64:65], 0, v[164:165]
	v_cvt_pk_bf16_f32 v64, v76, v77
	v_add_f32_e32 v66, v66, v67
	v_mul_f32_e32 v67, v73, v73
	v_mul_f32_e32 v76, v75, v75
	v_fmac_f32_e32 v67, v72, v72
	v_fmac_f32_e32 v76, v74, v74
	v_add_f32_e32 v67, v67, v76
	v_add_f32_e32 v66, v66, v67
	v_mul_f32_e32 v67, v69, v69
	v_mul_f32_e32 v76, v71, v71
	v_fmac_f32_e32 v67, v68, v68
	v_fmac_f32_e32 v76, v70, v70
	v_add_f32_e32 v67, v67, v76
	v_mul_f32_e32 v76, v91, v91
	v_mul_f32_e32 v77, v93, v93
	v_fmac_f32_e32 v76, v90, v90
	v_fmac_f32_e32 v77, v92, v92
	v_add_f32_e32 v76, v76, v77
	v_add_f32_e32 v67, v67, v76
	v_add_f32_e32 v76, v66, v67
	ds_bpermute_b32 v77, v174, v76
	v_cvt_pk_bf16_f32 v65, v78, v79
	v_cvt_pk_bf16_f32 v66, v72, v73
	v_cvt_pk_bf16_f32 v67, v74, v75
	global_store_dwordx4 v[94:95], v[64:67], off
	s_waitcnt lgkmcnt(0)
	s_nop 0
	v_add_f32_e32 v64, v76, v77
	ds_bpermute_b32 v65, v169, v64
	v_cvt_pk_bf16_f32 v66, v68, v69
	v_cvt_pk_bf16_f32 v67, v70, v71
	v_cvt_pk_bf16_f32 v68, v90, v91
	v_cvt_pk_bf16_f32 v69, v92, v93
	global_store_dwordx4 v[94:95], v[66:69], off offset:64
	s_and_saveexec_b64 s[0:1], vcc
	s_cbranch_execz .LBB0_652
	s_add_u32 s4, s6, s9
	s_addc_u32 s5, s7, s8
	s_waitcnt lgkmcnt(0)
	v_add_f32_e32 v66, v64, v65
	v_lshl_add_u64 v[64:65], v[160:161], 2, s[4:5]
	global_store_dword v[64:65], v66, off offset:192
